# v56 plus 64-bit accumulator zero-init (64 v_mov_b64 per tile), loop alignment preserved
# speedup vs baseline: 1.0023x; 1.0023x over previous
;     __device__ __forceinline__ bool next(int i, Unit& u) const { u.z = 0; return o.tile(i, u); }
;     __device__ __forceinline__ long a_off(const Unit& u) const { return (long)u.pm * tA; }
;     __device__ __forceinline__ long b_off(const Unit& u) const { return (long)u.pn * tB; }
;     __device__ __forceinline__ bool next(int i, Unit& u) const { u.z = i & 1; return o.tile(i >> 1, u); }
;     __device__ __forceinline__ long a_off(const Unit& u) const { return (long)u.pm * 256 * DM * 2 + (long)u.z * 512 * 2; }
;     __device__ __forceinline__ long b_off(const Unit& u) const { return ((long)u.z * 1024 + (long)u.pn * 256) * 512 * 2; }
;     __device__ __forceinline__ bool next(int i, Unit& u) const { u.z = 0; return o.tile(i, u); }
;     __device__ __forceinline__ long a_off(const Unit& u) const { const int ti = u.pm; const int b = ti / 65, i = ti % 65; return ((long)b * SEQ + 254 * i - 2) * DM * 2; }
;     __device__ __forceinline__ long b_off(const Unit& u) const { return (long)u.pn * 256 * DM * 2; }
; template <class Epi, class Sched>
; __device__ __forceinline__ void gemm_phase(LAS unsigned char* lds, const Gemm g, const Sched& S, const Epi& E) {
;     ...
;     for (;;) {
;         const bool has_next = S.next(ui + 1, nxt);
;         const char* nA = has_next ? (const char*)g.A + S.a_off(nxt) : cA; const char* nB = has_next ? (const char*)g.Bt + S.b_off(nxt) : cB;
;         for (int t = 0; t < nt; t += 2) {
;             const bool last = (t == nt - 2);
;             const char* a1 = cA + (size_t)(t + 1) * kstep;
;             const char* a2 = last ? nA : cA + (size_t)(t + 2) * kstep; const char* b2 = last ? nB : cB + (size_t)(t + 2) * kstep;
;     ...
; #pragma unroll
;         for (int a = 0; a < 2; ++a)
; #pragma unroll
;             for (int b = 0; b < 2; ++b)
; #pragma unroll
;                 for (int m = 0; m < 4; ++m)
; #pragma unroll
;                     for (int n = 0; n < 2; ++n) acc[a][b][m][n] = (f32x4){0.f, 0.f, 0.f, 0.f};
;         }
;         cur = nxt; cA = nA; cB = nB; ++ui;
.LBB0_173:
	s_ashr_i32 s15, s14, 31
	s_lshl_b64 s[16:17], s[14:15], 19
	s_add_u32 s16, s90, s16
	s_addc_u32 s17, s91, s17
	s_and_b64 s[18:19], s[40:41], exec
	s_cselect_b32 s15, s17, s21
	s_cselect_b32 s42, s16, s20
	s_ashr_i32 s13, s12, 31
	s_lshl_b64 s[18:19], s[12:13], 19
	v_readlane_b32 s13, v246, 16
	s_add_u32 s18, s13, s18
	v_readlane_b32 s13, v246, 17
	s_addc_u32 s19, s13, s19
	s_and_b64 s[22:23], s[40:41], exec
	s_cselect_b32 s13, s19, s1
	s_cselect_b32 s43, s18, s0
	s_add_u32 s51, s0, 0x100
	s_addc_u32 s54, s1, 0
	s_add_u32 s0, s20, 0x40080
	v_mov_b32_e32 v0, 0
	s_addc_u32 s1, s21, 0
	s_mov_b32 s55, -2
	v_mov_b64_e32 v[0:1], 0
	v_mov_b64_e32 v[2:3], 0
	v_mov_b64_e32 v[4:5], 0
	v_mov_b64_e32 v[6:7], 0
	v_mov_b64_e32 v[8:9], 0
	v_mov_b64_e32 v[10:11], 0
	v_mov_b64_e32 v[12:13], 0
	v_mov_b64_e32 v[14:15], 0
	v_mov_b64_e32 v[16:17], 0
	v_mov_b64_e32 v[18:19], 0
	v_mov_b64_e32 v[20:21], 0
	v_mov_b64_e32 v[22:23], 0
	v_mov_b64_e32 v[24:25], 0
	v_mov_b64_e32 v[26:27], 0
	v_mov_b64_e32 v[28:29], 0
	v_mov_b64_e32 v[30:31], 0
	v_mov_b64_e32 v[36:37], 0
	v_mov_b64_e32 v[38:39], 0
	v_mov_b64_e32 v[48:49], 0
	v_mov_b64_e32 v[50:51], 0
	v_mov_b64_e32 v[56:57], 0
	v_mov_b64_e32 v[58:59], 0
	v_mov_b64_e32 v[60:61], 0
	v_mov_b64_e32 v[62:63], 0
	v_mov_b64_e32 v[64:65], 0
	v_mov_b64_e32 v[66:67], 0
	v_mov_b64_e32 v[68:69], 0
	v_mov_b64_e32 v[70:71], 0
	v_mov_b64_e32 v[72:73], 0
	v_mov_b64_e32 v[74:75], 0
	v_mov_b64_e32 v[76:77], 0
	v_mov_b64_e32 v[78:79], 0
	v_mov_b64_e32 v[80:81], 0
	v_mov_b64_e32 v[82:83], 0
	v_mov_b64_e32 v[84:85], 0
	v_mov_b64_e32 v[86:87], 0
	v_mov_b64_e32 v[88:89], 0
	v_mov_b64_e32 v[90:91], 0
	v_mov_b64_e32 v[92:93], 0
	v_mov_b64_e32 v[94:95], 0
	v_mov_b64_e32 v[98:99], 0
	v_mov_b64_e32 v[100:101], 0
	v_mov_b64_e32 v[102:103], 0
	v_mov_b64_e32 v[104:105], 0
	v_mov_b64_e32 v[106:107], 0
	v_mov_b64_e32 v[108:109], 0
	v_mov_b64_e32 v[110:111], 0
	v_mov_b64_e32 v[112:113], 0
	v_mov_b64_e32 v[114:115], 0
	v_mov_b64_e32 v[116:117], 0
	v_mov_b64_e32 v[118:119], 0
	v_mov_b64_e32 v[120:121], 0
	v_mov_b64_e32 v[122:123], 0
	v_mov_b64_e32 v[124:125], 0
	v_mov_b64_e32 v[126:127], 0
	v_mov_b64_e32 v[128:129], 0
	v_mov_b64_e32 v[130:131], 0
	v_mov_b64_e32 v[132:133], 0
	v_mov_b64_e32 v[134:135], 0
	v_mov_b64_e32 v[136:137], 0
	v_mov_b64_e32 v[138:139], 0
	v_mov_b64_e32 v[140:141], 0
	v_mov_b64_e32 v[142:143], 0
	v_mov_b64_e32 v[144:145], 0
	s_nop 0
	s_nop 0
	s_nop 0
	s_nop 0
	s_nop 0
	s_nop 0
	s_nop 0
	s_nop 0
	s_nop 0
	s_nop 0
	s_nop 0
	s_nop 0
	s_nop 0
	s_nop 0
	s_nop 0
	s_nop 0
	s_nop 0
	s_nop 0
	s_nop 0
	s_nop 0
	s_nop 0
	s_nop 0
	s_nop 0
	s_nop 0
	s_nop 0
	s_nop 0
	s_nop 0

;     __device__ __forceinline__ bool next(int i, Unit& u) const { u.z = 0; return o.tile(i, u); }
;     __device__ __forceinline__ long a_off(const Unit& u) const { return (long)u.pm * tA; }
;     __device__ __forceinline__ long b_off(const Unit& u) const { return (long)u.pn * tB; }
;     __device__ __forceinline__ bool next(int i, Unit& u) const { u.z = i & 1; return o.tile(i >> 1, u); }
;     __device__ __forceinline__ long a_off(const Unit& u) const { return (long)u.pm * 256 * DM * 2 + (long)u.z * 512 * 2; }
;     __device__ __forceinline__ long b_off(const Unit& u) const { return ((long)u.z * 1024 + (long)u.pn * 256) * 512 * 2; }
;     __device__ __forceinline__ bool next(int i, Unit& u) const { u.z = 0; return o.tile(i, u); }
;     __device__ __forceinline__ long a_off(const Unit& u) const { const int ti = u.pm; const int b = ti / 65, i = ti % 65; return ((long)b * SEQ + 254 * i - 2) * DM * 2; }
;     __device__ __forceinline__ long b_off(const Unit& u) const { return (long)u.pn * 256 * DM * 2; }
; template <class Epi, class Sched>
; __device__ __forceinline__ void gemm_phase(LAS unsigned char* lds, const Gemm g, const Sched& S, const Epi& E) {
;     ...
;     for (;;) {
;         const bool has_next = S.next(ui + 1, nxt);
;         const char* nA = has_next ? (const char*)g.A + S.a_off(nxt) : cA; const char* nB = has_next ? (const char*)g.Bt + S.b_off(nxt) : cB;
;         for (int t = 0; t < nt; t += 2) {
;             const bool last = (t == nt - 2);
;             const char* a1 = cA + (size_t)(t + 1) * kstep;
;             const char* a2 = last ? nA : cA + (size_t)(t + 2) * kstep; const char* b2 = last ? nB : cB + (size_t)(t + 2) * kstep;
;     ...
; #pragma unroll
;         for (int a = 0; a < 2; ++a)
; #pragma unroll
;             for (int b = 0; b < 2; ++b)
; #pragma unroll
;                 for (int m = 0; m < 4; ++m)
; #pragma unroll
;                     for (int n = 0; n < 2; ++n) acc[a][b][m][n] = (f32x4){0.f, 0.f, 0.f, 0.f};
;         }
;         cur = nxt; cA = nA; cB = nB; ++ui;
.LBB0_878:
	s_ashr_i32 s15, s14, 31
	s_lshl_b64 s[16:17], s[14:15], 19
	s_add_u32 s16, s54, s16
	s_addc_u32 s17, s55, s17
	s_and_b64 s[18:19], s[46:47], exec
	s_cselect_b32 s15, s17, s21
	s_cselect_b32 s49, s16, s20
	s_ashr_i32 s13, s12, 31
	s_lshl_b64 s[18:19], s[12:13], 19
	s_add_u32 s18, s40, s18
	s_addc_u32 s19, s41, s19
	s_and_b64 s[22:23], s[46:47], exec
	s_cselect_b32 s13, s19, s1
	s_cselect_b32 s50, s18, s0
	s_add_u32 s51, s0, 0x100
	s_addc_u32 s56, s1, 0
	s_add_u32 s0, s20, 0x40080
	v_mov_b32_e32 v0, 0
	s_addc_u32 s1, s21, 0
	s_mov_b32 s57, -2
	s_waitcnt lgkmcnt(0)
	v_mov_b64_e32 v[0:1], 0
	v_mov_b64_e32 v[2:3], 0
	v_mov_b64_e32 v[4:5], 0
	v_mov_b64_e32 v[6:7], 0
	v_mov_b64_e32 v[8:9], 0
	v_mov_b64_e32 v[10:11], 0
	v_mov_b64_e32 v[12:13], 0
	v_mov_b64_e32 v[14:15], 0
	v_mov_b64_e32 v[16:17], 0
	v_mov_b64_e32 v[18:19], 0
	v_mov_b64_e32 v[20:21], 0
	v_mov_b64_e32 v[22:23], 0
	v_mov_b64_e32 v[24:25], 0
	v_mov_b64_e32 v[26:27], 0
	v_mov_b64_e32 v[28:29], 0
	v_mov_b64_e32 v[30:31], 0
	v_mov_b64_e32 v[32:33], 0
	v_mov_b64_e32 v[34:35], 0
	v_mov_b64_e32 v[36:37], 0
	v_mov_b64_e32 v[38:39], 0
	v_mov_b64_e32 v[40:41], 0
	v_mov_b64_e32 v[42:43], 0
	v_mov_b64_e32 v[44:45], 0
	v_mov_b64_e32 v[46:47], 0
	v_mov_b64_e32 v[48:49], 0
	v_mov_b64_e32 v[50:51], 0
	v_mov_b64_e32 v[52:53], 0
	v_mov_b64_e32 v[54:55], 0
	v_mov_b64_e32 v[56:57], 0
	v_mov_b64_e32 v[58:59], 0
	v_mov_b64_e32 v[60:61], 0
	v_mov_b64_e32 v[62:63], 0
	v_mov_b64_e32 v[64:65], 0
	v_mov_b64_e32 v[66:67], 0
	v_mov_b64_e32 v[68:69], 0
	v_mov_b64_e32 v[70:71], 0
	v_mov_b64_e32 v[72:73], 0
	v_mov_b64_e32 v[74:75], 0
	v_mov_b64_e32 v[76:77], 0
	v_mov_b64_e32 v[78:79], 0
	v_mov_b64_e32 v[80:81], 0
	v_mov_b64_e32 v[82:83], 0
	v_mov_b64_e32 v[84:85], 0
	v_mov_b64_e32 v[86:87], 0
	v_mov_b64_e32 v[88:89], 0
	v_mov_b64_e32 v[90:91], 0
	v_mov_b64_e32 v[92:93], 0
	v_mov_b64_e32 v[94:95], 0
	v_mov_b64_e32 v[98:99], 0
	v_mov_b64_e32 v[100:101], 0
	v_mov_b64_e32 v[102:103], 0
	v_mov_b64_e32 v[104:105], 0
	v_mov_b64_e32 v[106:107], 0
	v_mov_b64_e32 v[108:109], 0
	v_mov_b64_e32 v[110:111], 0
	v_mov_b64_e32 v[112:113], 0
	v_mov_b64_e32 v[114:115], 0
	v_mov_b64_e32 v[116:117], 0
	v_mov_b64_e32 v[122:123], 0
	v_mov_b64_e32 v[124:125], 0
	v_mov_b64_e32 v[130:131], 0
	v_mov_b64_e32 v[132:133], 0
	v_mov_b64_e32 v[142:143], 0
	v_mov_b64_e32 v[144:145], 0
	s_nop 0
	s_nop 0
	s_nop 0
	s_nop 0
	s_nop 0
	s_nop 0
	s_nop 0
	s_nop 0
	s_nop 0
	s_nop 0
	s_nop 0
	s_nop 0
	s_nop 0
	s_nop 0
	s_nop 0
	s_nop 0
	s_nop 0
	s_nop 0
	s_nop 0

;     __device__ __forceinline__ bool next(int i, Unit& u) const { u.z = 0; return o.tile(i, u); }
;     __device__ __forceinline__ long a_off(const Unit& u) const { return (long)u.pm * tA; }
;     __device__ __forceinline__ long b_off(const Unit& u) const { return (long)u.pn * tB; }
;     __device__ __forceinline__ bool next(int i, Unit& u) const { u.z = i & 1; return o.tile(i >> 1, u); }
;     __device__ __forceinline__ long a_off(const Unit& u) const { return (long)u.pm * 256 * DM * 2 + (long)u.z * 512 * 2; }
;     __device__ __forceinline__ long b_off(const Unit& u) const { return ((long)u.z * 1024 + (long)u.pn * 256) * 512 * 2; }
;     __device__ __forceinline__ bool next(int i, Unit& u) const { u.z = 0; return o.tile(i, u); }
;     __device__ __forceinline__ long a_off(const Unit& u) const { const int ti = u.pm; const int b = ti / 65, i = ti % 65; return ((long)b * SEQ + 254 * i - 2) * DM * 2; }
;     __device__ __forceinline__ long b_off(const Unit& u) const { return (long)u.pn * 256 * DM * 2; }
; template <class Epi, class Sched>
; __device__ __forceinline__ void gemm_phase(LAS unsigned char* lds, const Gemm g, const Sched& S, const Epi& E) {
;     ...
;     for (;;) {
;         const bool has_next = S.next(ui + 1, nxt);
;         const char* nA = has_next ? (const char*)g.A + S.a_off(nxt) : cA; const char* nB = has_next ? (const char*)g.Bt + S.b_off(nxt) : cB;
;         for (int t = 0; t < nt; t += 2) {
;             const bool last = (t == nt - 2);
;             const char* a1 = cA + (size_t)(t + 1) * kstep;
;             const char* a2 = last ? nA : cA + (size_t)(t + 2) * kstep; const char* b2 = last ? nB : cB + (size_t)(t + 2) * kstep;
;     ...
; #pragma unroll
;         for (int a = 0; a < 2; ++a)
; #pragma unroll
;             for (int b = 0; b < 2; ++b)
; #pragma unroll
;                 for (int m = 0; m < 4; ++m)
; #pragma unroll
;                     for (int n = 0; n < 2; ++n) acc[a][b][m][n] = (f32x4){0.f, 0.f, 0.f, 0.f};
;         }
;         cur = nxt; cA = nA; cB = nB; ++ui;
.LBB0_923:
	s_ashr_i32 s15, s14, 31
	s_lshl_b64 s[16:17], s[14:15], 19
	s_add_u32 s16, s54, s16
	s_addc_u32 s17, s55, s17
	s_and_b64 s[18:19], s[46:47], exec
	s_cselect_b32 s15, s17, s21
	s_cselect_b32 s49, s16, s20
	s_ashr_i32 s13, s12, 31
	s_lshl_b64 s[18:19], s[12:13], 19
	s_add_u32 s18, s40, s18
	s_addc_u32 s19, s41, s19
	s_and_b64 s[22:23], s[46:47], exec
	s_cselect_b32 s13, s19, s1
	s_cselect_b32 s50, s18, s0
	s_add_u32 s51, s0, 0x100
	s_addc_u32 s56, s1, 0
	s_add_u32 s0, s20, 0x40080
	v_mov_b32_e32 v0, 0
	s_addc_u32 s1, s21, 0
	s_mov_b32 s57, -2
	s_waitcnt lgkmcnt(0)
	v_mov_b64_e32 v[0:1], 0
	v_mov_b64_e32 v[2:3], 0
	v_mov_b64_e32 v[4:5], 0
	v_mov_b64_e32 v[6:7], 0
	v_mov_b64_e32 v[8:9], 0
	v_mov_b64_e32 v[10:11], 0
	v_mov_b64_e32 v[12:13], 0
	v_mov_b64_e32 v[14:15], 0
	v_mov_b64_e32 v[16:17], 0
	v_mov_b64_e32 v[18:19], 0
	v_mov_b64_e32 v[20:21], 0
	v_mov_b64_e32 v[22:23], 0
	v_mov_b64_e32 v[24:25], 0
	v_mov_b64_e32 v[26:27], 0
	v_mov_b64_e32 v[28:29], 0
	v_mov_b64_e32 v[30:31], 0
	v_mov_b64_e32 v[32:33], 0
	v_mov_b64_e32 v[34:35], 0
	v_mov_b64_e32 v[36:37], 0
	v_mov_b64_e32 v[38:39], 0
	v_mov_b64_e32 v[40:41], 0
	v_mov_b64_e32 v[42:43], 0
	v_mov_b64_e32 v[44:45], 0
	v_mov_b64_e32 v[46:47], 0
	v_mov_b64_e32 v[48:49], 0
	v_mov_b64_e32 v[50:51], 0
	v_mov_b64_e32 v[52:53], 0
	v_mov_b64_e32 v[54:55], 0
	v_mov_b64_e32 v[56:57], 0
	v_mov_b64_e32 v[58:59], 0
	v_mov_b64_e32 v[60:61], 0
	v_mov_b64_e32 v[62:63], 0
	v_mov_b64_e32 v[64:65], 0
	v_mov_b64_e32 v[66:67], 0
	v_mov_b64_e32 v[68:69], 0
	v_mov_b64_e32 v[70:71], 0
	v_mov_b64_e32 v[72:73], 0
	v_mov_b64_e32 v[74:75], 0
	v_mov_b64_e32 v[76:77], 0
	v_mov_b64_e32 v[78:79], 0
	v_mov_b64_e32 v[80:81], 0
	v_mov_b64_e32 v[82:83], 0
	v_mov_b64_e32 v[84:85], 0
	v_mov_b64_e32 v[86:87], 0
	v_mov_b64_e32 v[88:89], 0
	v_mov_b64_e32 v[90:91], 0
	v_mov_b64_e32 v[92:93], 0
	v_mov_b64_e32 v[94:95], 0
	v_mov_b64_e32 v[98:99], 0
	v_mov_b64_e32 v[100:101], 0
	v_mov_b64_e32 v[102:103], 0
	v_mov_b64_e32 v[104:105], 0
	v_mov_b64_e32 v[106:107], 0
	v_mov_b64_e32 v[108:109], 0
	v_mov_b64_e32 v[110:111], 0
	v_mov_b64_e32 v[112:113], 0
	v_mov_b64_e32 v[114:115], 0
	v_mov_b64_e32 v[116:117], 0
	v_mov_b64_e32 v[118:119], 0
	v_mov_b64_e32 v[120:121], 0
	v_mov_b64_e32 v[122:123], 0
	v_mov_b64_e32 v[124:125], 0
	v_mov_b64_e32 v[126:127], 0
	v_mov_b64_e32 v[128:129], 0
	s_nop 0
	s_nop 0
	s_nop 0
	s_nop 0
	s_nop 0
	s_nop 0
	s_nop 0
	s_nop 0
	s_nop 0
	s_nop 0
	s_nop 0
	s_nop 0
	s_nop 0
	s_nop 0
	s_nop 0
	s_nop 0
	s_nop 0
	s_nop 0
	s_nop 0
	s_nop 0

;     __device__ __forceinline__ bool next(int i, Unit& u) const { u.z = 0; return o.tile(i, u); }
;     __device__ __forceinline__ long a_off(const Unit& u) const { return (long)u.pm * tA; }
;     __device__ __forceinline__ long b_off(const Unit& u) const { return (long)u.pn * tB; }
;     __device__ __forceinline__ bool next(int i, Unit& u) const { u.z = i & 1; return o.tile(i >> 1, u); }
;     __device__ __forceinline__ long a_off(const Unit& u) const { return (long)u.pm * 256 * DM * 2 + (long)u.z * 512 * 2; }
;     __device__ __forceinline__ long b_off(const Unit& u) const { return ((long)u.z * 1024 + (long)u.pn * 256) * 512 * 2; }
;     __device__ __forceinline__ bool next(int i, Unit& u) const { u.z = 0; return o.tile(i, u); }
;     __device__ __forceinline__ long a_off(const Unit& u) const { const int ti = u.pm; const int b = ti / 65, i = ti % 65; return ((long)b * SEQ + 254 * i - 2) * DM * 2; }
;     __device__ __forceinline__ long b_off(const Unit& u) const { return (long)u.pn * 256 * DM * 2; }
; template <class Epi, class Sched>
; __device__ __forceinline__ void gemm_phase(LAS unsigned char* lds, const Gemm g, const Sched& S, const Epi& E) {
;     ...
;     for (;;) {
;         const bool has_next = S.next(ui + 1, nxt);
;         const char* nA = has_next ? (const char*)g.A + S.a_off(nxt) : cA; const char* nB = has_next ? (const char*)g.Bt + S.b_off(nxt) : cB;
;         for (int t = 0; t < nt; t += 2) {
;             const bool last = (t == nt - 2);
;             const char* a1 = cA + (size_t)(t + 1) * kstep;
;             const char* a2 = last ? nA : cA + (size_t)(t + 2) * kstep; const char* b2 = last ? nB : cB + (size_t)(t + 2) * kstep;
;     ...
; #pragma unroll
;         for (int a = 0; a < 2; ++a)
; #pragma unroll
;             for (int b = 0; b < 2; ++b)
; #pragma unroll
;                 for (int m = 0; m < 4; ++m)
; #pragma unroll
;                     for (int n = 0; n < 2; ++n) acc[a][b][m][n] = (f32x4){0.f, 0.f, 0.f, 0.f};
;         }
;         cur = nxt; cA = nA; cB = nB; ++ui;
.LBB0_1024:
	s_ashr_i32 s9, s8, 31
	s_lshl_b64 s[10:11], s[8:9], 19
	s_add_u32 s10, s90, s10
	s_addc_u32 s11, s91, s11
	s_and_b64 s[12:13], s[46:47], exec
	s_cselect_b32 s9, s11, s19
	s_cselect_b32 s17, s10, s18
	s_ashr_i32 s3, s2, 31
	s_lshl_b64 s[12:13], s[2:3], 19
	v_readlane_b32 s3, v246, 26
	s_add_u32 s12, s3, s12
	v_readlane_b32 s3, v246, 27
	s_addc_u32 s13, s3, s13
	s_and_b64 s[20:21], s[46:47], exec
	s_cselect_b32 s3, s13, s15
	s_cselect_b32 s23, s12, s14
	s_add_u32 s48, s14, 0x100
	s_addc_u32 s49, s15, 0
	s_add_u32 s14, s18, 0x40080
	v_mov_b32_e32 v20, 0
	s_addc_u32 s15, s19, 0
	s_mov_b32 s50, -2
	v_mov_b64_e32 v[0:1], 0
	v_mov_b64_e32 v[2:3], 0
	v_mov_b64_e32 v[4:5], 0
	v_mov_b64_e32 v[6:7], 0
	v_mov_b64_e32 v[8:9], 0
	v_mov_b64_e32 v[10:11], 0
	v_mov_b64_e32 v[12:13], 0
	v_mov_b64_e32 v[14:15], 0
	v_mov_b64_e32 v[16:17], 0
	v_mov_b64_e32 v[18:19], 0
	v_mov_b64_e32 v[20:21], 0
	v_mov_b64_e32 v[22:23], 0
	v_mov_b64_e32 v[24:25], 0
	v_mov_b64_e32 v[26:27], 0
	v_mov_b64_e32 v[28:29], 0
	v_mov_b64_e32 v[30:31], 0
	v_mov_b64_e32 v[32:33], 0
	v_mov_b64_e32 v[34:35], 0
	v_mov_b64_e32 v[36:37], 0
	v_mov_b64_e32 v[38:39], 0
	v_mov_b64_e32 v[40:41], 0
	v_mov_b64_e32 v[42:43], 0
	v_mov_b64_e32 v[44:45], 0
	v_mov_b64_e32 v[46:47], 0
	v_mov_b64_e32 v[48:49], 0
	v_mov_b64_e32 v[50:51], 0
	v_mov_b64_e32 v[52:53], 0
	v_mov_b64_e32 v[54:55], 0
	v_mov_b64_e32 v[56:57], 0
	v_mov_b64_e32 v[58:59], 0
	v_mov_b64_e32 v[60:61], 0
	v_mov_b64_e32 v[62:63], 0
	v_mov_b64_e32 v[64:65], 0
	v_mov_b64_e32 v[66:67], 0
	v_mov_b64_e32 v[68:69], 0
	v_mov_b64_e32 v[70:71], 0
	v_mov_b64_e32 v[72:73], 0
	v_mov_b64_e32 v[74:75], 0
	v_mov_b64_e32 v[76:77], 0
	v_mov_b64_e32 v[78:79], 0
	v_mov_b64_e32 v[114:115], 0
	v_mov_b64_e32 v[116:117], 0
	v_mov_b64_e32 v[118:119], 0
	v_mov_b64_e32 v[120:121], 0
	v_mov_b64_e32 v[122:123], 0
	v_mov_b64_e32 v[124:125], 0
	v_mov_b64_e32 v[128:129], 0
	v_mov_b64_e32 v[130:131], 0
	v_mov_b64_e32 v[132:133], 0
	v_mov_b64_e32 v[134:135], 0
	v_mov_b64_e32 v[136:137], 0
	v_mov_b64_e32 v[138:139], 0
	v_mov_b64_e32 v[140:141], 0
	v_mov_b64_e32 v[142:143], 0
	v_mov_b64_e32 v[144:145], 0
	v_mov_b64_e32 v[146:147], 0
	v_mov_b64_e32 v[148:149], 0
	v_mov_b64_e32 v[150:151], 0
	v_mov_b64_e32 v[152:153], 0
	v_mov_b64_e32 v[154:155], 0
	v_mov_b64_e32 v[156:157], 0
	v_mov_b64_e32 v[158:159], 0
	v_mov_b64_e32 v[160:161], 0
	v_mov_b64_e32 v[162:163], 0
	s_nop 0
	s_nop 0
	s_nop 0
	s_nop 0
	s_nop 0
	s_nop 0
	s_nop 0
	s_nop 0
	s_nop 0
	s_nop 0
	s_nop 0
	s_nop 0
	s_nop 0
	s_nop 0
	s_nop 0
	s_nop 0
	s_nop 0

;     __device__ __forceinline__ bool next(int i, Unit& u) const { u.z = 0; return o.tile(i, u); }
;     __device__ __forceinline__ long a_off(const Unit& u) const { return (long)u.pm * tA; }
;     __device__ __forceinline__ long b_off(const Unit& u) const { return (long)u.pn * tB; }
;     __device__ __forceinline__ bool next(int i, Unit& u) const { u.z = i & 1; return o.tile(i >> 1, u); }
;     __device__ __forceinline__ long a_off(const Unit& u) const { return (long)u.pm * 256 * DM * 2 + (long)u.z * 512 * 2; }
;     __device__ __forceinline__ long b_off(const Unit& u) const { return ((long)u.z * 1024 + (long)u.pn * 256) * 512 * 2; }
;     __device__ __forceinline__ bool next(int i, Unit& u) const { u.z = 0; return o.tile(i, u); }
;     __device__ __forceinline__ long a_off(const Unit& u) const { const int ti = u.pm; const int b = ti / 65, i = ti % 65; return ((long)b * SEQ + 254 * i - 2) * DM * 2; }
;     __device__ __forceinline__ long b_off(const Unit& u) const { return (long)u.pn * 256 * DM * 2; }
; template <class Epi, class Sched>
; __device__ __forceinline__ void gemm_phase(LAS unsigned char* lds, const Gemm g, const Sched& S, const Epi& E) {
;     ...
;     for (;;) {
;         const bool has_next = S.next(ui + 1, nxt);
;         const char* nA = has_next ? (const char*)g.A + S.a_off(nxt) : cA; const char* nB = has_next ? (const char*)g.Bt + S.b_off(nxt) : cB;
;         for (int t = 0; t < nt; t += 2) {
;             const bool last = (t == nt - 2);
;             const char* a1 = cA + (size_t)(t + 1) * kstep;
;             const char* a2 = last ? nA : cA + (size_t)(t + 2) * kstep; const char* b2 = last ? nB : cB + (size_t)(t + 2) * kstep;
;     ...
; #pragma unroll
;         for (int a = 0; a < 2; ++a)
; #pragma unroll
;             for (int b = 0; b < 2; ++b)
; #pragma unroll
;                 for (int m = 0; m < 4; ++m)
; #pragma unroll
;                     for (int n = 0; n < 2; ++n) acc[a][b][m][n] = (f32x4){0.f, 0.f, 0.f, 0.f};
;         }
;         cur = nxt; cA = nA; cB = nB; ++ui;
.LBB0_1241:
	s_add_u32 s45, s14, 0x100
	v_mov_b32_e32 v0, 0
	s_addc_u32 s48, s15, 0
	s_mov_b32 s49, -2
	v_mov_b64_e32 v[0:1], 0
	v_mov_b64_e32 v[2:3], 0
	v_mov_b64_e32 v[4:5], 0
	v_mov_b64_e32 v[6:7], 0
	v_mov_b64_e32 v[8:9], 0
	v_mov_b64_e32 v[10:11], 0
	v_mov_b64_e32 v[12:13], 0
	v_mov_b64_e32 v[14:15], 0
	v_mov_b64_e32 v[16:17], 0
	v_mov_b64_e32 v[18:19], 0
	v_mov_b64_e32 v[20:21], 0
	v_mov_b64_e32 v[22:23], 0
	v_mov_b64_e32 v[24:25], 0
	v_mov_b64_e32 v[26:27], 0
	v_mov_b64_e32 v[28:29], 0
	v_mov_b64_e32 v[30:31], 0
	v_mov_b64_e32 v[32:33], 0
	v_mov_b64_e32 v[34:35], 0
	v_mov_b64_e32 v[36:37], 0
	v_mov_b64_e32 v[38:39], 0
	v_mov_b64_e32 v[40:41], 0
	v_mov_b64_e32 v[42:43], 0
	v_mov_b64_e32 v[44:45], 0
	v_mov_b64_e32 v[46:47], 0
	v_mov_b64_e32 v[48:49], 0
	v_mov_b64_e32 v[50:51], 0
	v_mov_b64_e32 v[52:53], 0
	v_mov_b64_e32 v[54:55], 0
	v_mov_b64_e32 v[56:57], 0
	v_mov_b64_e32 v[58:59], 0
	v_mov_b64_e32 v[60:61], 0
	v_mov_b64_e32 v[62:63], 0
	v_mov_b64_e32 v[64:65], 0
	v_mov_b64_e32 v[66:67], 0
	v_mov_b64_e32 v[68:69], 0
	v_mov_b64_e32 v[70:71], 0
	v_mov_b64_e32 v[72:73], 0
	v_mov_b64_e32 v[74:75], 0
	v_mov_b64_e32 v[76:77], 0
	v_mov_b64_e32 v[78:79], 0
	v_mov_b64_e32 v[80:81], 0
	v_mov_b64_e32 v[82:83], 0
	v_mov_b64_e32 v[84:85], 0
	v_mov_b64_e32 v[86:87], 0
	v_mov_b64_e32 v[88:89], 0
	v_mov_b64_e32 v[90:91], 0
	v_mov_b64_e32 v[92:93], 0
	v_mov_b64_e32 v[94:95], 0
	v_mov_b64_e32 v[98:99], 0
	v_mov_b64_e32 v[100:101], 0
	v_mov_b64_e32 v[102:103], 0
	v_mov_b64_e32 v[104:105], 0
	v_mov_b64_e32 v[106:107], 0
	v_mov_b64_e32 v[108:109], 0
	v_mov_b64_e32 v[110:111], 0
	v_mov_b64_e32 v[112:113], 0
	v_mov_b64_e32 v[114:115], 0
	v_mov_b64_e32 v[116:117], 0
	v_mov_b64_e32 v[118:119], 0
	v_mov_b64_e32 v[120:121], 0
	v_mov_b64_e32 v[122:123], 0
	v_mov_b64_e32 v[124:125], 0
	v_mov_b64_e32 v[126:127], 0
	v_mov_b64_e32 v[128:129], 0
	s_nop 0
	s_nop 0
	s_nop 0
	s_nop 0
	s_nop 0
	s_nop 0
	s_nop 0
	s_nop 0
	s_nop 0
	s_nop 0
	s_nop 0
	s_nop 0
	s_nop 0
	s_nop 0
	s_nop 0
	s_nop 0
	s_nop 0
	s_nop 0

;     __device__ __forceinline__ bool next(int i, Unit& u) const { u.z = 0; return o.tile(i, u); }
;     __device__ __forceinline__ long a_off(const Unit& u) const { return (long)u.pm * tA; }
;     __device__ __forceinline__ long b_off(const Unit& u) const { return (long)u.pn * tB; }
;     __device__ __forceinline__ bool next(int i, Unit& u) const { u.z = i & 1; return o.tile(i >> 1, u); }
;     __device__ __forceinline__ long a_off(const Unit& u) const { return (long)u.pm * 256 * DM * 2 + (long)u.z * 512 * 2; }
;     __device__ __forceinline__ long b_off(const Unit& u) const { return ((long)u.z * 1024 + (long)u.pn * 256) * 512 * 2; }
;     __device__ __forceinline__ bool next(int i, Unit& u) const { u.z = 0; return o.tile(i, u); }
;     __device__ __forceinline__ long a_off(const Unit& u) const { const int ti = u.pm; const int b = ti / 65, i = ti % 65; return ((long)b * SEQ + 254 * i - 2) * DM * 2; }
;     __device__ __forceinline__ long b_off(const Unit& u) const { return (long)u.pn * 256 * DM * 2; }
; template <class Epi, class Sched>
; __device__ __forceinline__ void gemm_phase(LAS unsigned char* lds, const Gemm g, const Sched& S, const Epi& E) {
;     ...
;     for (;;) {
;         const bool has_next = S.next(ui + 1, nxt);
;         const char* nA = has_next ? (const char*)g.A + S.a_off(nxt) : cA; const char* nB = has_next ? (const char*)g.Bt + S.b_off(nxt) : cB;
;         for (int t = 0; t < nt; t += 2) {
;             const bool last = (t == nt - 2);
;             const char* a1 = cA + (size_t)(t + 1) * kstep;
;             const char* a2 = last ? nA : cA + (size_t)(t + 2) * kstep; const char* b2 = last ? nB : cB + (size_t)(t + 2) * kstep;
;     ...
; #pragma unroll
;         for (int a = 0; a < 2; ++a)
; #pragma unroll
;             for (int b = 0; b < 2; ++b)
; #pragma unroll
;                 for (int m = 0; m < 4; ++m)
; #pragma unroll
;                     for (int n = 0; n < 2; ++n) acc[a][b][m][n] = (f32x4){0.f, 0.f, 0.f, 0.f};
;         }
;         cur = nxt; cA = nA; cB = nB; ++ui;
.LBB0_1274:
	s_add_u32 s49, s18, 0x100
	v_mov_b32_e32 v0, 0
	s_addc_u32 s50, s19, 0
	s_mov_b32 s51, -2
	s_waitcnt lgkmcnt(0)
	v_mov_b64_e32 v[0:1], 0
	v_mov_b64_e32 v[2:3], 0
	v_mov_b64_e32 v[4:5], 0
	v_mov_b64_e32 v[6:7], 0
	v_mov_b64_e32 v[8:9], 0
	v_mov_b64_e32 v[10:11], 0
	v_mov_b64_e32 v[12:13], 0
	v_mov_b64_e32 v[14:15], 0
	v_mov_b64_e32 v[16:17], 0
	v_mov_b64_e32 v[18:19], 0
	v_mov_b64_e32 v[20:21], 0
	v_mov_b64_e32 v[22:23], 0
	v_mov_b64_e32 v[24:25], 0
	v_mov_b64_e32 v[26:27], 0
	v_mov_b64_e32 v[28:29], 0
	v_mov_b64_e32 v[30:31], 0
	v_mov_b64_e32 v[32:33], 0
	v_mov_b64_e32 v[34:35], 0
	v_mov_b64_e32 v[36:37], 0
	v_mov_b64_e32 v[38:39], 0
	v_mov_b64_e32 v[40:41], 0
	v_mov_b64_e32 v[42:43], 0
	v_mov_b64_e32 v[44:45], 0
	v_mov_b64_e32 v[46:47], 0
	v_mov_b64_e32 v[48:49], 0
	v_mov_b64_e32 v[50:51], 0
	v_mov_b64_e32 v[52:53], 0
	v_mov_b64_e32 v[54:55], 0
	v_mov_b64_e32 v[56:57], 0
	v_mov_b64_e32 v[58:59], 0
	v_mov_b64_e32 v[60:61], 0
	v_mov_b64_e32 v[62:63], 0
	v_mov_b64_e32 v[64:65], 0
	v_mov_b64_e32 v[66:67], 0
	v_mov_b64_e32 v[68:69], 0
	v_mov_b64_e32 v[70:71], 0
	v_mov_b64_e32 v[72:73], 0
	v_mov_b64_e32 v[74:75], 0
	v_mov_b64_e32 v[76:77], 0
	v_mov_b64_e32 v[78:79], 0
	v_mov_b64_e32 v[80:81], 0
	v_mov_b64_e32 v[82:83], 0
	v_mov_b64_e32 v[84:85], 0
	v_mov_b64_e32 v[86:87], 0
	v_mov_b64_e32 v[88:89], 0
	v_mov_b64_e32 v[90:91], 0
	v_mov_b64_e32 v[92:93], 0
	v_mov_b64_e32 v[94:95], 0
	v_mov_b64_e32 v[98:99], 0
	v_mov_b64_e32 v[100:101], 0
	v_mov_b64_e32 v[102:103], 0
	v_mov_b64_e32 v[104:105], 0
	v_mov_b64_e32 v[106:107], 0
	v_mov_b64_e32 v[108:109], 0
	v_mov_b64_e32 v[110:111], 0
	v_mov_b64_e32 v[112:113], 0
	v_mov_b64_e32 v[114:115], 0
	v_mov_b64_e32 v[116:117], 0
	v_mov_b64_e32 v[122:123], 0
	v_mov_b64_e32 v[124:125], 0
	v_mov_b64_e32 v[130:131], 0
	v_mov_b64_e32 v[132:133], 0
	v_mov_b64_e32 v[142:143], 0
	v_mov_b64_e32 v[144:145], 0
	s_nop 0
	s_nop 0
	s_nop 0
	s_nop 0
	s_nop 0
	s_nop 0
	s_nop 0
	s_nop 0
	s_nop 0
	s_nop 0
	s_nop 0
	s_nop 0
	s_nop 0
	s_nop 0
	s_nop 0
	s_nop 0
	s_nop 0
	s_nop 0
	s_nop 0
	s_nop 0
	s_nop 0
	s_nop 0
	s_nop 0
	s_nop 0
	s_nop 0
	s_nop 0
	s_nop 0
	s_nop 0
	s_nop 0
